# State scan mid barrier: output-tile LDS writes issued ahead of fifteen of the fragment reads with a counted wait, so the reads complete under the barrier and the state conversions
# speedup vs baseline: 1.0034x; 1.0034x over previous
.LBB0_433:
	s_mul_i32 s1, s0, 37
	s_bfe_u32 s2, s1, 0x80008
	s_lshr_b32 s1, s1, 8
	s_sub_i32 s1, s0, s1
	s_bfe_u32 s1, s1, 0x70001
	s_add_i32 s1, s1, s2
	s_bfe_u32 s1, s1, 0x60002
	s_mul_i32 s1, s1, 7
	s_sub_i32 s1, s0, s1
	s_and_b32 s1, s1, 0xff
	s_mulk_i32 s1, 0x4800
	v_add_u32_e32 v136, s1, v151
	ds_read_b128 v[228:231], v136 offset:17792
	ds_read_b128 v[232:235], v136 offset:17824
	ds_read_b128 v[236:239], v136 offset:17856
	ds_read_b128 v[240:243], v136 offset:17888
	ds_read_b128 v[128:131], v136 offset:17920
	ds_read_b128 v[132:135], v136 offset:17952
	ds_read_b128 v[220:223], v136 offset:17984
	ds_read_b128 v[224:227], v136 offset:18016
	v_cvt_pk_bf16_f32 v112, v16, v17
	v_cvt_pk_bf16_f32 v113, v18, v19
	v_cvt_pk_bf16_f32 v114, v20, v21
	v_cvt_pk_bf16_f32 v115, v22, v23
	v_cvt_pk_bf16_f32 v116, v24, v25
	v_cvt_pk_bf16_f32 v117, v26, v27
	v_cvt_pk_bf16_f32 v118, v28, v29
	v_cvt_pk_bf16_f32 v119, v30, v31
	s_nop 1
	v_mfma_f32_32x32x16_bf16 v[32:47], v[48:51], v[112:115], 0
	v_mfma_f32_32x32x16_bf16 v[32:47], v[52:55], v[116:119], v[32:47]
	v_cvt_pk_bf16_f32 v120, v0, v1
	v_cvt_pk_bf16_f32 v121, v2, v3
	v_cvt_pk_bf16_f32 v122, v4, v5
	v_cvt_pk_bf16_f32 v123, v6, v7
	v_cvt_pk_bf16_f32 v124, v8, v9
	v_cvt_pk_bf16_f32 v125, v10, v11
	v_cvt_pk_bf16_f32 v126, v12, v13
	v_cvt_pk_bf16_f32 v127, v14, v15
	s_waitcnt lgkmcnt(0)
	v_pk_mul_f32 v[16:17], v[16:17], v[228:229]
	v_pk_mul_f32 v[18:19], v[18:19], v[230:231]
	v_pk_mul_f32 v[20:21], v[20:21], v[232:233]
	v_pk_mul_f32 v[22:23], v[22:23], v[234:235]
	v_pk_mul_f32 v[24:25], v[24:25], v[236:237]
	v_pk_mul_f32 v[26:27], v[26:27], v[238:239]
	v_pk_mul_f32 v[28:29], v[28:29], v[240:241]
	v_pk_mul_f32 v[30:31], v[30:31], v[242:243]
	v_mul_f32_e64 v0, v0, v128
	v_mul_f32_e64 v1, v1, v129
	v_mul_f32_e64 v2, v2, v130
	v_mul_f32_e64 v3, v3, v131
	v_mul_f32_e64 v4, v4, v132
	v_mul_f32_e64 v5, v5, v133
	v_pk_mul_f32 v[6:7], v[6:7], v[134:135]
	s_or_b32 s1, s0, 1
	v_mfma_f32_32x32x16_bf16 v[16:31], v[72:75], v[112:115], v[16:31]
	s_and_b32 s2, s1, 0xff
	v_mul_f32_e64 v8, v8, v220
	v_mul_f32_e64 v9, v9, v221
	v_mul_f32_e64 v10, v10, v222
	v_mul_f32_e64 v11, v11, v223
	v_pk_mul_f32 v[12:13], v[12:13], v[224:225]
	v_pk_mul_f32 v[14:15], v[14:15], v[226:227]
	s_mul_i32 s2, s2, 37
	s_lshr_b32 s2, s2, 8
	s_sub_i32 s3, s1, s2
	s_bfe_u32 s3, s3, 0x70001
	s_add_i32 s3, s3, s2
	s_lshr_b32 s2, s3, 2
	s_mul_i32 s2, s2, 7
	s_sub_i32 s1, s1, s2
	s_and_b32 s1, s1, 0xff
	v_mfma_f32_32x32x16_bf16 v[0:15], v[88:91], v[112:115], v[0:15]
	s_mulk_i32 s1, 0x4800
	s_add_i32 s1, s1, 0
	v_add_u32_e32 v192, s1, v144
	v_add_u32_e32 v180, v192, v156
	s_cmpk_gt_u32 s0, 0x7d
	s_cselect_b64 s[2:3], -1, 0
	v_mfma_f32_32x32x16_bf16 v[16:31], v[76:79], v[116:119], v[16:31]
	s_and_b64 vcc, exec, s[2:3]
	v_mfma_f32_32x32x16_bf16 v[32:47], v[56:59], v[120:123], v[32:47]
	v_mfma_f32_32x32x16_bf16 v[0:15], v[92:95], v[116:119], v[0:15]
	v_mfma_f32_32x32x16_bf16 v[16:31], v[80:83], v[120:123], v[16:31]
	v_mfma_f32_32x32x16_bf16 v[32:47], v[60:63], v[124:127], v[32:47]
	v_mfma_f32_32x32x16_bf16 v[0:15], v[96:99], v[120:123], v[0:15]
	v_mfma_f32_32x32x16_bf16 v[16:31], v[84:87], v[124:127], v[16:31]
	v_mfma_f32_32x32x16_bf16 v[32:47], v[68:71], v[64:67], v[32:47]
	v_mfma_f32_32x32x16_bf16 v[0:15], v[100:103], v[124:127], v[0:15]
	s_nop 10
	v_add_u32_e32 v45, s1, v153
	v_add_u32_e32 v46, v45, v152
	v_add_u32_e32 v160, v45, v155
	v_add_u32_e32 v44, v192, v150
	ds_read2_b64 v[40:43], v46 offset1:2
	ds_read2_b64 v[116:119], v46 offset0:4 offset1:6
	ds_read2_b64 v[120:123], v46 offset0:8 offset1:10
	ds_read2_b64 v[124:127], v46 offset0:12 offset1:14
	v_add_u32_e32 v46, v192, v154
	v_add_u32_e32 v132, 0x800, v160
	v_mfma_f32_32x32x16_bf16 v[16:31], v[104:107], v[64:67], v[16:31]
	v_add_u32_e32 v172, 0x1800, v160
	ds_read_b128 v[112:115], v44 offset:14720
	ds_read_b128 v[128:131], v46 offset:2176
	ds_read2_b64 v[44:47], v132 offset0:112 offset1:114
	ds_read2_b64 v[140:143], v132 offset0:116 offset1:118
	ds_write2st64_b32 v158, v32, v33 offset1:1
	ds_write2st64_b32 v158, v34, v35 offset0:2 offset1:3
	ds_write2st64_b32 v158, v36, v37 offset0:8 offset1:9
	ds_write2st64_b32 v158, v38, v39 offset0:10 offset1:11
	ds_read2_b64 v[136:139], v132 offset0:120 offset1:122
	ds_read2_b64 v[132:135], v132 offset0:124 offset1:126
	ds_read2_b64 v[160:163], v172 offset0:144 offset1:146
	ds_read2_b64 v[164:167], v172 offset0:148 offset1:150
	ds_read2_b64 v[168:171], v172 offset0:152 offset1:154
	ds_read2_b64 v[172:175], v172 offset0:156 offset1:158
	ds_read_b128 v[176:179], v180 offset:11648
	ds_read_b128 v[180:183], v180 offset:13184
	ds_read_b128 v[220:223], v192 offset:17888
	ds_read_b128 v[224:227], v192 offset:17856
	ds_read_b128 v[228:231], v192 offset:17824
	ds_read_b128 v[232:235], v192 offset:17792
	ds_read_b128 v[236:239], v192 offset:18016
	ds_read_b128 v[240:243], v192 offset:17984
	ds_read_b128 v[244:247], v192 offset:17952
	s_waitcnt lgkmcnt(15)
	s_barrier
	ds_read_b128 v[36:39], v192 offset:17920
	v_cvt_pk_bf16_f32 v32, v16, v17
	v_mfma_f32_32x32x16_bf16 v[0:15], v[108:111], v[64:67], v[0:15]
	v_cvt_pk_bf16_f32 v33, v18, v19
	v_cvt_pk_bf16_f32 v34, v20, v21
	v_cvt_pk_bf16_f32 v35, v22, v23
	v_cvt_pk_bf16_f32 v184, v24, v25
	v_cvt_pk_bf16_f32 v185, v26, v27
	v_cvt_pk_bf16_f32 v186, v28, v29
	v_cvt_pk_bf16_f32 v187, v30, v31
	v_cvt_pk_bf16_f32 v188, v0, v1
	v_cvt_pk_bf16_f32 v189, v2, v3
	v_cvt_pk_bf16_f32 v190, v4, v5
	v_cvt_pk_bf16_f32 v191, v6, v7
	v_cvt_pk_bf16_f32 v216, v8, v9
	v_cvt_pk_bf16_f32 v217, v10, v11
	v_cvt_pk_bf16_f32 v218, v12, v13
	v_cvt_pk_bf16_f32 v219, v14, v15
	s_waitcnt lgkmcnt(1)
	v_pk_mul_f32 v[28:29], v[28:29], v[220:221]
	v_pk_mul_f32 v[30:31], v[30:31], v[222:223]
	v_pk_mul_f32 v[24:25], v[24:25], v[224:225]
	v_pk_mul_f32 v[26:27], v[26:27], v[226:227]
	v_pk_mul_f32 v[20:21], v[20:21], v[228:229]
	v_pk_mul_f32 v[22:23], v[22:23], v[230:231]
	v_pk_mul_f32 v[18:19], v[18:19], v[234:235]
	v_pk_mul_f32 v[16:17], v[16:17], v[232:233]
	v_pk_mul_f32 v[12:13], v[12:13], v[236:237]
	v_pk_mul_f32 v[14:15], v[14:15], v[238:239]
	v_mfma_f32_32x32x16_bf16 v[16:31], v[44:47], v[32:35], v[16:31]
	v_mul_f32_e64 v8, v8, v240
	v_mul_f32_e64 v9, v9, v241
	v_mul_f32_e64 v10, v10, v242
	v_mul_f32_e64 v11, v11, v243
	v_pk_mul_f32 v[4:5], v[4:5], v[244:245]
	v_pk_mul_f32 v[6:7], v[6:7], v[246:247]
	v_mfma_f32_32x32x16_bf16 v[16:31], v[140:143], v[184:187], v[16:31]
	s_waitcnt lgkmcnt(0)
	v_mul_f32_e64 v2, v2, v38
	v_mul_f32_e64 v3, v3, v39
	v_mul_f32_e64 v0, v0, v36
	v_mul_f32_e64 v1, v1, v37
	s_nop 1
	v_mfma_f32_32x32x16_bf16 v[0:15], v[160:163], v[32:35], v[0:15]
	v_mfma_f32_32x32x16_bf16 v[32:47], v[40:43], v[32:35], 0
	v_mfma_f32_32x32x16_bf16 v[32:47], v[116:119], v[184:187], v[32:47]
	v_mfma_f32_32x32x16_bf16 v[0:15], v[164:167], v[184:187], v[0:15]
	v_mfma_f32_32x32x16_bf16 v[32:47], v[120:123], v[188:191], v[32:47]
	v_mfma_f32_32x32x16_bf16 v[16:31], v[136:139], v[188:191], v[16:31]
	v_mfma_f32_32x32x16_bf16 v[0:15], v[168:171], v[188:191], v[0:15]
	v_mfma_f32_32x32x16_bf16 v[32:47], v[124:127], v[216:219], v[32:47]
	v_mfma_f32_32x32x16_bf16 v[16:31], v[132:135], v[216:219], v[16:31]
	v_mfma_f32_32x32x16_bf16 v[0:15], v[172:175], v[216:219], v[0:15]
	v_mfma_f32_32x32x16_bf16 v[32:47], v[128:131], v[112:115], v[32:47]
	v_mfma_f32_32x32x16_bf16 v[16:31], v[176:179], v[112:115], v[16:31]
	v_mfma_f32_32x32x16_bf16 v[0:15], v[180:183], v[112:115], v[0:15]
	s_cbranch_vccnz .LBB0_432
	s_add_i32 s1, s0, 2
	s_and_b32 s4, s1, 0xff
	s_mul_i32 s4, s4, 37
	s_lshr_b32 s5, s4, 8
	s_sub_i32 s5, s1, s5
	s_bfe_u32 s5, s5, 0x70001
	s_bfe_u32 s4, s4, 0x80008
	s_add_i32 s5, s5, s4
	s_bfe_u32 s4, s5, 0x60002
	s_mul_i32 s4, s4, 7
	s_sub_i32 s1, s1, s4
	s_and_b32 s1, s1, 0xff
	s_mulk_i32 s1, 0x4800
	s_add_i32 s1, s1, 0
	v_add_u32_e32 v40, s1, v144
	v_add_u32_e32 v42, s1, v153
	v_add_u32_e32 v41, v40, v150
	v_add_u32_e32 v43, v42, v152
	ds_read2_b64 v[48:51], v43 offset1:2
	ds_read2_b64 v[52:55], v43 offset0:4 offset1:6
	ds_read2_b64 v[56:59], v43 offset0:8 offset1:10
	ds_read2_b64 v[60:63], v43 offset0:12 offset1:14
	v_add_u32_e32 v43, v40, v154
	ds_read_b128 v[64:67], v41 offset:14720
	ds_read_b128 v[68:71], v43 offset:2176
	v_add_u32_e32 v41, v42, v155
	v_add_u32_e32 v42, 0x800, v41
	v_add_u32_e32 v41, 0x1800, v41
	ds_read2_b64 v[72:75], v42 offset0:112 offset1:114
	ds_read2_b64 v[76:79], v42 offset0:116 offset1:118
	ds_read2_b64 v[80:83], v42 offset0:120 offset1:122
	ds_read2_b64 v[84:87], v42 offset0:124 offset1:126
	v_add_u32_e32 v40, v40, v156
	ds_read2_b64 v[88:91], v41 offset0:144 offset1:146
	ds_read2_b64 v[92:95], v41 offset0:148 offset1:150
	ds_read2_b64 v[96:99], v41 offset0:152 offset1:154
	ds_read2_b64 v[100:103], v41 offset0:156 offset1:158
	ds_read_b128 v[104:107], v40 offset:11648
	ds_read_b128 v[108:111], v40 offset:13184
	s_branch .LBB0_432
